# band attention step loop: dropped counted lgkmcnt waits before the QK^T MFMAs that the previous step's closing lgkmcnt(0)+barrier already covers, on top of the head-GEMM drain removal and rope load ho
# baseline (speedup 1.0000x reference)
.LBB0_637:
	s_lshl_b64 s[28:29], s[2:3], s22
	v_lshl_add_u64 v[64:65], s[28:29], 1, v[180:181]
	s_add_i32 s0, s4, s75
	s_mov_b32 s28, m0
	s_mov_b32 m0, s0
	s_nop 0
	global_load_lds_dwordx4 v[64:65], off
	s_mov_b32 m0, s28
	s_sub_i32 s28, s23, 0x80
	s_max_i32 s28, s28, 0
	s_sub_i32 s29, s76, 63
	s_cmp_le_i32 s29, s28
	s_cbranch_scc1 .Lxa_idle
	s_sub_i32 s29, s76, 0xde
	s_cmp_gt_i32 s29, s23
	s_cbranch_scc1 .Lxa_idle
	v_add_u32_e32 v164, s1, v190
	ds_read_b64_tr_b16 v[160:161], v164 offset:24576
	ds_read_b64_tr_b16 v[162:163], v164 offset:25088
	v_mfma_f32_32x32x16_bf16 v[80:95], v[156:159], v[124:127], 0
	v_add_f32_e32 v64, v48, v49
	v_add_f32_e32 v64, v50, v64
	v_add_f32_e32 v64, v51, v64
	v_add_f32_e32 v64, v52, v64
	v_add_f32_e32 v64, v53, v64
	v_cvt_pk_bf16_f32 v116, v48, v49
	v_cvt_pk_bf16_f32 v117, v50, v51
	ds_read_b64_tr_b16 v[156:157], v164 offset:28672
	ds_read_b64_tr_b16 v[158:159], v164 offset:29184
	v_add_f32_e32 v48, v54, v64
	v_mfma_f32_32x32x16_bf16 v[64:79], v[148:151], v[124:127], 0
	v_add_f32_e32 v48, v55, v48
	v_add_f32_e32 v48, v56, v48
	v_add_f32_e32 v96, v57, v48
	v_cvt_pk_bf16_f32 v118, v52, v53
	v_cvt_pk_bf16_f32 v119, v54, v55
	ds_read_b64_tr_b16 v[48:49], v164 offset:25600
	ds_read_b64_tr_b16 v[50:51], v164 offset:26112
	v_mfma_f32_32x32x16_bf16 v[80:95], v[152:155], v[120:123], v[80:95]
	v_add_f32_e32 v52, v58, v96
	v_add_f32_e32 v52, v59, v52
	v_add_f32_e32 v52, v60, v52
	v_add_f32_e32 v96, v61, v52
	v_cvt_pk_bf16_f32 v108, v56, v57
	v_cvt_pk_bf16_f32 v109, v58, v59
	ds_read_b64_tr_b16 v[52:53], v164 offset:29696
	ds_read_b64_tr_b16 v[54:55], v164 offset:30208
	v_mfma_f32_32x32x16_bf16 v[64:79], v[144:147], v[120:123], v[64:79]
	v_add_f32_e32 v56, v62, v96
	v_add_f32_e32 v56, v63, v56
	v_add_f32_e32 v56, v32, v56
	v_add_f32_e32 v96, v33, v56
	v_cvt_pk_bf16_f32 v110, v60, v61
	v_cvt_pk_bf16_f32 v111, v62, v63
	ds_read_b64_tr_b16 v[56:57], v164 offset:26624
	ds_read_b64_tr_b16 v[58:59], v164 offset:27136
	v_mfma_f32_32x32x16_bf16 v[80:95], v[140:143], v[112:115], v[80:95]
	v_add_f32_e32 v60, v34, v96
	v_add_f32_e32 v60, v35, v60
	v_add_f32_e32 v60, v36, v60
	v_add_f32_e32 v60, v37, v60
	v_cvt_pk_bf16_f32 v100, v32, v33
	v_cvt_pk_bf16_f32 v101, v34, v35
	ds_read_b64_tr_b16 v[32:33], v164 offset:30720
	ds_read_b64_tr_b16 v[34:35], v164 offset:31232
	v_mfma_f32_32x32x16_bf16 v[64:79], v[136:139], v[112:115], v[64:79]
	v_add_f32_e32 v60, v38, v60
	v_add_f32_e32 v60, v39, v60
	v_add_f32_e32 v60, v40, v60
	v_add_f32_e32 v60, v41, v60
	v_cvt_pk_bf16_f32 v102, v36, v37
	v_cvt_pk_bf16_f32 v103, v38, v39
	ds_read_b64_tr_b16 v[36:37], v164 offset:27648
	ds_read_b64_tr_b16 v[38:39], v164 offset:28160
	v_mfma_f32_32x32x16_bf16 v[80:95], v[132:135], v[104:107], v[80:95]
	v_add_f32_e32 v60, v42, v60
	v_add_f32_e32 v60, v43, v60
	v_add_f32_e32 v60, v44, v60
	v_add_f32_e32 v60, v45, v60
	v_cvt_pk_bf16_f32 v96, v40, v41
	v_cvt_pk_bf16_f32 v97, v42, v43
	ds_read_b64_tr_b16 v[40:41], v164 offset:31744
	ds_read_b64_tr_b16 v[42:43], v164 offset:32256
	v_mfma_f32_32x32x16_bf16 v[64:79], v[128:131], v[104:107], v[64:79]
	v_add_f32_e32 v60, v46, v60
	v_add_f32_e32 v60, v47, v60
	v_add_f32_e32 v191, 0, v60
	v_cvt_pk_bf16_f32 v98, v44, v45
	v_cvt_pk_bf16_f32 v99, v46, v47
	v_add_u32_e32 v203, s76, v184
	s_sub_i32 s0, s76, 64
	v_add_u32_e32 v149, 0xffffff81, v203
	s_cmp_le_i32 s0, s23
	v_sub_u32_e32 v150, v203, v186
	v_sub_u32_e32 v148, v203, v187
	v_subrev_u32_e32 v150, 68, v150
	v_subrev_u32_e32 v148, 68, v148
	s_cbranch_scc1 .LBB0_641
	v_cmp_le_i32_e64 s[0:1], v150, 27
	v_cmp_le_i32_e64 s[38:39], v150, 26
	v_cmp_le_i32_e64 s[40:41], v150, 25
	v_cmp_le_i32_e64 s[42:43], v150, 24
	v_cmp_le_i32_e64 s[44:45], v150, 19
	v_cmp_le_i32_e64 s[46:47], v150, 18
	v_cmp_le_i32_e64 s[50:51], v150, 17
	v_cmp_le_i32_e64 s[52:53], v150, 16
	v_cmp_le_i32_e64 s[54:55], v150, 11
	v_cmp_le_i32_e64 s[56:57], v150, 10
	v_cmp_le_i32_e64 s[58:59], v150, 9
	v_cmp_le_i32_e64 s[60:61], v150, 8
	v_cmp_le_i32_e64 s[62:63], v150, 3
	v_cmp_le_i32_e64 s[64:65], v150, 2
	v_cmp_le_i32_e64 s[66:67], v150, 1
	v_cmp_le_i32_e32 vcc, v149, v186
	v_cndmask_b32_e64 v64, v240, v64, s[0:1]
	v_cmp_lt_i32_e64 s[0:1], v149, v186
	v_cndmask_b32_e64 v65, v240, v65, s[38:39]
	v_cmp_le_i32_e64 s[38:39], v150, 57
	v_cndmask_b32_e64 v66, v240, v66, s[40:41]
	v_cmp_le_i32_e64 s[40:41], v150, 56
	v_cndmask_b32_e64 v67, v240, v67, s[42:43]
	v_cmp_le_i32_e64 s[42:43], v150, 51
	v_cndmask_b32_e64 v68, v240, v68, s[44:45]
	v_cmp_le_i32_e64 s[44:45], v150, 50
	v_cndmask_b32_e64 v69, v240, v69, s[46:47]
	v_cmp_le_i32_e64 s[46:47], v150, 49
	v_cndmask_b32_e64 v70, v240, v70, s[50:51]
	v_cmp_le_i32_e64 s[50:51], v150, 48
	v_cndmask_b32_e64 v71, v240, v71, s[52:53]
	v_cmp_le_i32_e64 s[52:53], v150, 43
	v_cndmask_b32_e64 v72, v240, v72, s[54:55]
	v_cmp_le_i32_e64 s[54:55], v150, 42
	v_cndmask_b32_e64 v73, v240, v73, s[56:57]
	v_cmp_le_i32_e64 s[56:57], v150, 41
	v_cndmask_b32_e64 v74, v240, v74, s[58:59]
	v_cmp_le_i32_e64 s[58:59], v150, 40
	v_cndmask_b32_e64 v75, v240, v75, s[60:61]
	v_cmp_le_i32_e64 s[60:61], v150, 35
	v_cndmask_b32_e64 v76, v240, v76, s[62:63]
	v_cmp_le_i32_e64 s[62:63], v150, 34
	v_cndmask_b32_e64 v77, v240, v77, s[64:65]
	v_cmp_le_i32_e64 s[64:65], v150, 33
	v_cndmask_b32_e64 v78, v240, v78, s[66:67]
	v_cmp_le_i32_e64 s[66:67], v150, 32
	v_cmp_gt_i32_e64 s[68:69], v150, 0
	s_and_saveexec_b64 s[28:29], s[68:69]
	s_mov_b32 s68, 0xff800000
	v_mov_b32_e32 v79, s68
	s_or_b64 exec, exec, s[28:29]
	v_cndmask_b32_e64 v81, v240, v81, s[0:1]
	v_cndmask_b32_e32 v80, v240, v80, vcc
	v_cndmask_b32_e64 v82, v240, v82, s[38:39]
	v_cndmask_b32_e64 v83, v240, v83, s[40:41]
	v_cndmask_b32_e64 v84, v240, v84, s[42:43]
	v_cndmask_b32_e64 v85, v240, v85, s[44:45]
	v_cndmask_b32_e64 v86, v240, v86, s[46:47]
	v_cndmask_b32_e64 v87, v240, v87, s[50:51]
	v_cndmask_b32_e64 v88, v240, v88, s[52:53]
	v_cndmask_b32_e64 v89, v240, v89, s[54:55]
	v_cndmask_b32_e64 v90, v240, v90, s[56:57]
	v_cndmask_b32_e64 v91, v240, v91, s[58:59]
	v_cndmask_b32_e64 v92, v240, v92, s[60:61]
	v_cndmask_b32_e64 v93, v240, v93, s[62:63]
	v_cndmask_b32_e64 v94, v240, v94, s[64:65]
	v_cndmask_b32_e64 v95, v240, v95, s[66:67]

.LBB0_657:
	s_sub_i32 s0, s23, 0x80
	s_max_i32 s0, s0, 0
	s_add_i32 s1, s76, 1
	s_cmp_le_i32 s1, s0
	s_cbranch_scc1 .Lxb_idle
	s_sub_i32 s1, s76, 0x9e
	s_cmp_gt_i32 s1, s23
	s_cbranch_scc1 .Lxb_idle
	v_add_u32_e32 v194, s72, v190
	ds_read_b64_tr_b16 v[168:169], v194 offset:24576
	ds_read_b64_tr_b16 v[170:171], v194 offset:25088
	v_mfma_f32_32x32x16_bf16 v[48:63], v[156:159], v[124:127], 0
	v_add_f32_e32 v32, v80, v81
	v_add_f32_e32 v32, v82, v32
	v_add_f32_e32 v32, v83, v32
	v_add_f32_e32 v32, v84, v32
	v_add_f32_e32 v32, v85, v32
	v_cvt_pk_bf16_f32 v116, v80, v81
	v_cvt_pk_bf16_f32 v117, v82, v83
	ds_read_b64_tr_b16 v[164:165], v194 offset:28672
	ds_read_b64_tr_b16 v[166:167], v194 offset:29184
	v_add_f32_e32 v32, v86, v32
	v_add_f32_e32 v32, v87, v32
	v_add_f32_e32 v32, v88, v32
	v_add_f32_e32 v80, v89, v32
	v_mfma_f32_32x32x16_bf16 v[32:47], v[148:151], v[124:127], 0
	v_cvt_pk_bf16_f32 v118, v84, v85
	v_cvt_pk_bf16_f32 v119, v86, v87
	ds_read_b64_tr_b16 v[160:161], v194 offset:25600
	ds_read_b64_tr_b16 v[162:163], v194 offset:26112
	v_mfma_f32_32x32x16_bf16 v[48:63], v[152:155], v[120:123], v[48:63]
	v_add_f32_e32 v80, v90, v80
	v_add_f32_e32 v80, v91, v80
	v_add_f32_e32 v80, v92, v80
	v_add_f32_e32 v80, v93, v80
	v_cvt_pk_bf16_f32 v108, v88, v89
	v_cvt_pk_bf16_f32 v109, v90, v91
	ds_read_b64_tr_b16 v[88:89], v194 offset:29696
	ds_read_b64_tr_b16 v[90:91], v194 offset:30208
	v_mfma_f32_32x32x16_bf16 v[32:47], v[144:147], v[120:123], v[32:47]
	v_add_f32_e32 v80, v94, v80
	v_add_f32_e32 v80, v95, v80
	v_add_f32_e32 v80, v64, v80
	v_add_f32_e32 v80, v65, v80
	v_cvt_pk_bf16_f32 v110, v92, v93
	v_cvt_pk_bf16_f32 v111, v94, v95
	ds_read_b64_tr_b16 v[84:85], v194 offset:26624
	ds_read_b64_tr_b16 v[86:87], v194 offset:27136
	v_mfma_f32_32x32x16_bf16 v[48:63], v[140:143], v[112:115], v[48:63]
	v_add_f32_e32 v80, v66, v80
	v_add_f32_e32 v80, v67, v80
	v_add_f32_e32 v80, v68, v80
	v_add_f32_e32 v92, v69, v80
	v_cvt_pk_bf16_f32 v100, v64, v65
	v_cvt_pk_bf16_f32 v101, v66, v67
	ds_read_b64_tr_b16 v[80:81], v194 offset:30720
	ds_read_b64_tr_b16 v[82:83], v194 offset:31232
	v_mfma_f32_32x32x16_bf16 v[32:47], v[136:139], v[112:115], v[32:47]
	v_add_f32_e32 v64, v70, v92
	v_add_f32_e32 v64, v71, v64
	v_add_f32_e32 v64, v72, v64
	v_add_f32_e32 v64, v73, v64
	v_cvt_pk_bf16_f32 v102, v68, v69
	v_cvt_pk_bf16_f32 v103, v70, v71
	ds_read_b64_tr_b16 v[68:69], v194 offset:27648
	ds_read_b64_tr_b16 v[70:71], v194 offset:28160
	v_mfma_f32_32x32x16_bf16 v[48:63], v[132:135], v[104:107], v[48:63]
	v_add_f32_e32 v64, v74, v64
	v_add_f32_e32 v64, v75, v64
	v_add_f32_e32 v64, v76, v64
	v_add_f32_e32 v92, v77, v64
	v_cvt_pk_bf16_f32 v96, v72, v73
	v_cvt_pk_bf16_f32 v97, v74, v75
	ds_read_b64_tr_b16 v[64:65], v194 offset:31744
	ds_read_b64_tr_b16 v[66:67], v194 offset:32256
	v_mfma_f32_32x32x16_bf16 v[32:47], v[128:131], v[104:107], v[32:47]
	v_add_f32_e32 v72, v78, v92
	v_add_f32_e32 v72, v79, v72
	v_add_f32_e32 v72, 0, v72
	v_cvt_pk_bf16_f32 v98, v76, v77
	v_cvt_pk_bf16_f32 v99, v78, v79
	v_sub_u32_e32 v222, v203, v186
	v_sub_u32_e32 v223, v203, v187
	v_subrev_u32_e32 v222, 4, v222
	v_subrev_u32_e32 v223, 4, v223
	s_cmp_le_i32 s76, s23
	s_cbranch_scc1 .LBB0_661
	v_cmp_le_i32_e64 s[0:1], v222, 27
	v_cmp_le_i32_e64 s[38:39], v222, 26
	v_cmp_le_i32_e64 s[40:41], v222, 25
	v_cmp_le_i32_e64 s[42:43], v222, 24
	v_cmp_le_i32_e64 s[44:45], v222, 19
	v_cmp_le_i32_e64 s[46:47], v222, 18
	v_cmp_le_i32_e64 s[50:51], v222, 17
	v_cmp_le_i32_e64 s[52:53], v222, 16
	v_cmp_le_i32_e64 s[54:55], v222, 11
	v_cmp_le_i32_e64 s[56:57], v222, 10
	v_cmp_le_i32_e64 s[58:59], v222, 9
	v_cmp_le_i32_e64 s[60:61], v222, 8
	v_cmp_le_i32_e64 s[62:63], v222, 3
	v_cmp_le_i32_e64 s[64:65], v222, 2
	v_cmp_le_i32_e64 s[66:67], v222, 1
	v_cmp_ge_i32_e32 vcc, 59, v222
	v_cndmask_b32_e64 v32, v240, v32, s[0:1]
	v_cmp_lt_i32_e64 s[0:1], v222, 59
	v_cndmask_b32_e64 v33, v240, v33, s[38:39]
	v_cmp_le_i32_e64 s[38:39], v222, 57
	v_cndmask_b32_e64 v34, v240, v34, s[40:41]
	v_cmp_le_i32_e64 s[40:41], v222, 56
	v_cndmask_b32_e64 v35, v240, v35, s[42:43]
	v_cmp_le_i32_e64 s[42:43], v222, 51
	v_cndmask_b32_e64 v36, v240, v36, s[44:45]
	v_cmp_le_i32_e64 s[44:45], v222, 50
	v_cndmask_b32_e64 v37, v240, v37, s[46:47]
	v_cmp_le_i32_e64 s[46:47], v222, 49
	v_cndmask_b32_e64 v38, v240, v38, s[50:51]
	v_cmp_le_i32_e64 s[50:51], v222, 48
	v_cndmask_b32_e64 v39, v240, v39, s[52:53]
	v_cmp_le_i32_e64 s[52:53], v222, 43
	v_cndmask_b32_e64 v40, v240, v40, s[54:55]
	v_cmp_le_i32_e64 s[54:55], v222, 42
	v_cndmask_b32_e64 v41, v240, v41, s[56:57]
	v_cmp_le_i32_e64 s[56:57], v222, 41
	v_cndmask_b32_e64 v42, v240, v42, s[58:59]
	v_cmp_le_i32_e64 s[58:59], v222, 40
	v_cndmask_b32_e64 v43, v240, v43, s[60:61]
	v_cmp_le_i32_e64 s[60:61], v222, 35
	v_cndmask_b32_e64 v44, v240, v44, s[62:63]
	v_cmp_le_i32_e64 s[62:63], v222, 34
	v_cndmask_b32_e64 v45, v240, v45, s[64:65]
	v_cmp_le_i32_e64 s[64:65], v222, 33
	v_cndmask_b32_e64 v46, v240, v46, s[66:67]
	v_cmp_le_i32_e64 s[66:67], v222, 32
	v_cmp_gt_i32_e64 s[68:69], v222, 0
	s_and_saveexec_b64 s[72:73], s[68:69]
	s_mov_b32 s68, 0xff800000
	v_mov_b32_e32 v47, s68
	s_or_b64 exec, exec, s[72:73]
	v_cndmask_b32_e64 v49, v240, v49, s[0:1]
	v_cndmask_b32_e32 v48, v240, v48, vcc
	v_cndmask_b32_e64 v50, v240, v50, s[38:39]
	v_cndmask_b32_e64 v51, v240, v51, s[40:41]
	v_cndmask_b32_e64 v52, v240, v52, s[42:43]
	v_cndmask_b32_e64 v53, v240, v53, s[44:45]
	v_cndmask_b32_e64 v54, v240, v54, s[46:47]
	v_cndmask_b32_e64 v55, v240, v55, s[50:51]
	v_cndmask_b32_e64 v56, v240, v56, s[52:53]
	v_cndmask_b32_e64 v57, v240, v57, s[54:55]
	v_cndmask_b32_e64 v58, v240, v58, s[56:57]
	v_cndmask_b32_e64 v59, v240, v59, s[58:59]
	v_cndmask_b32_e64 v60, v240, v60, s[60:61]
	v_cndmask_b32_e64 v61, v240, v61, s[62:63]
	v_cndmask_b32_e64 v62, v240, v62, s[64:65]
	v_cndmask_b32_e64 v63, v240, v63, s[66:67]
